# LayerNorm+modulation phase: next row's shift/scale vectors loaded before the current row's stores into a second register set, counted vmcnt(4) instead of a per-row vmcnt(0) store drain
# speedup vs baseline: 1.0030x; 1.0030x over previous
.LBB0_161:
	s_ashr_i32 s9, s8, 31
	s_lshl_b64 s[8:9], s[8:9], 11
	v_lshl_add_u64 v[26:27], v[72:73], 0, s[8:9]
	s_waitcnt vmcnt(4)
	v_pk_add_f32 v[236:237], v[236:237], 1.0 op_sel_hi:[1,0]
	v_pk_add_f32 v[234:235], v[234:235], 1.0 op_sel_hi:[1,0]
	v_pk_fma_f32 v[16:17], v[16:17], v[236:237], v[220:221]
	v_pk_fma_f32 v[14:15], v[14:15], v[234:235], v[218:219]
	s_nop 0
	v_cvt_pk_bf16_f32 v14, v14, v15
	v_cvt_pk_bf16_f32 v15, v16, v17
	global_store_dwordx2 v[26:27], v[14:15], off
	v_pk_add_f32 v[240:241], v[240:241], 1.0 op_sel_hi:[1,0]
	v_pk_add_f32 v[238:239], v[238:239], 1.0 op_sel_hi:[1,0]
	v_pk_fma_f32 v[12:13], v[12:13], v[240:241], v[224:225]
	v_pk_fma_f32 v[10:11], v[10:11], v[238:239], v[222:223]
	s_nop 0
	v_cvt_pk_bf16_f32 v10, v10, v11
	v_cvt_pk_bf16_f32 v11, v12, v13
	global_store_dwordx2 v[26:27], v[10:11], off offset:512
	v_pk_add_f32 v[244:245], v[244:245], 1.0 op_sel_hi:[1,0]
	v_pk_add_f32 v[242:243], v[242:243], 1.0 op_sel_hi:[1,0]
	v_pk_fma_f32 v[4:5], v[4:5], v[244:245], v[228:229]
	v_pk_fma_f32 v[2:3], v[2:3], v[242:243], v[226:227]
	s_nop 0
	v_cvt_pk_bf16_f32 v2, v2, v3
	v_cvt_pk_bf16_f32 v3, v4, v5
	global_store_dwordx2 v[26:27], v[2:3], off offset:1024
	v_pk_add_f32 v[248:249], v[248:249], 1.0 op_sel_hi:[1,0]
	v_pk_add_f32 v[246:247], v[246:247], 1.0 op_sel_hi:[1,0]
	v_pk_fma_f32 v[8:9], v[8:9], v[248:249], v[232:233]
	v_pk_fma_f32 v[6:7], v[6:7], v[246:247], v[230:231]
	s_nop 0
	v_cvt_pk_bf16_f32 v6, v6, v7
	v_cvt_pk_bf16_f32 v7, v8, v9
	global_store_dwordx2 v[26:27], v[6:7], off offset:1536

.LBB0_167:
	s_min_i32 s0, s46, 0x8000
	s_ashr_i32 s0, s0, 12
	s_mulk_i32 s0, 0xc00
	s_ashr_i32 s1, s0, 31
	s_lshl_b64 s[0:1], s[0:1], 2
	s_add_u32 s0, s19, s0
	s_addc_u32 s1, s28, s1
	s_add_u32 s16, s0, 0x1000
	s_addc_u32 s17, s1, 0
	global_load_dwordx4 v[120:123], v0, s[0:1]
	global_load_dwordx4 v[124:127], v0, s[0:1] offset:1024
	global_load_dwordx4 v[128:131], v0, s[0:1] offset:2048
	global_load_dwordx4 v[132:135], v0, s[0:1] offset:3072
	global_load_dwordx4 v[136:139], v0, s[16:17]
	global_load_dwordx4 v[140:143], v0, s[16:17] offset:1024
	global_load_dwordx4 v[144:147], v0, s[16:17] offset:2048
	global_load_dwordx4 v[148:151], v0, s[16:17] offset:3072
	v_lshl_add_u64 v[88:89], s[90:91], 0, v[74:75]
	v_add_co_u32_e32 v88, vcc, s70, v88
	v_addc_co_u32_e32 v89, vcc, 0, v89, vcc
	s_waitcnt vmcnt(0)
	s_min_i32 s0, s49, 0x8000
	s_ashr_i32 s0, s0, 12
	s_mulk_i32 s0, 0xc00
	s_ashr_i32 s1, s0, 31
	s_lshl_b64 s[0:1], s[0:1], 2
	s_add_u32 s0, s19, s0
	s_addc_u32 s1, s28, s1
	s_add_u32 s16, s0, 0x1000
	s_addc_u32 s17, s1, 0
	global_load_dwordx4 v[218:221], v0, s[0:1]
	global_load_dwordx4 v[222:225], v0, s[0:1] offset:1024
	global_load_dwordx4 v[226:229], v0, s[0:1] offset:2048
	global_load_dwordx4 v[230:233], v0, s[0:1] offset:3072
	global_load_dwordx4 v[234:237], v0, s[16:17]
	global_load_dwordx4 v[238:241], v0, s[16:17] offset:1024
	global_load_dwordx4 v[242:245], v0, s[16:17] offset:2048
	global_load_dwordx4 v[246:249], v0, s[16:17] offset:3072
	v_pk_add_f32 v[138:139], v[138:139], 1.0 op_sel_hi:[1,0]
	v_pk_add_f32 v[136:137], v[136:137], 1.0 op_sel_hi:[1,0]
	v_pk_fma_f32 v[64:65], v[64:65], v[138:139], v[122:123]
	v_pk_fma_f32 v[62:63], v[62:63], v[136:137], v[120:121]
	s_nop 0
	v_cvt_pk_bf16_f32 v62, v62, v63
	v_cvt_pk_bf16_f32 v63, v64, v65
	global_store_dwordx2 v[88:89], v[62:63], off
	v_pk_add_f32 v[142:143], v[142:143], 1.0 op_sel_hi:[1,0]
	v_pk_add_f32 v[140:141], v[140:141], 1.0 op_sel_hi:[1,0]
	v_pk_fma_f32 v[60:61], v[60:61], v[142:143], v[126:127]
	v_pk_fma_f32 v[58:59], v[58:59], v[140:141], v[124:125]
	s_nop 0
	v_cvt_pk_bf16_f32 v58, v58, v59
	v_cvt_pk_bf16_f32 v59, v60, v61
	global_store_dwordx2 v[88:89], v[58:59], off offset:512
	v_pk_add_f32 v[146:147], v[146:147], 1.0 op_sel_hi:[1,0]
	v_pk_add_f32 v[144:145], v[144:145], 1.0 op_sel_hi:[1,0]
	v_pk_fma_f32 v[56:57], v[56:57], v[146:147], v[130:131]
	v_pk_fma_f32 v[54:55], v[54:55], v[144:145], v[128:129]
	s_nop 0
	v_cvt_pk_bf16_f32 v54, v54, v55
	v_cvt_pk_bf16_f32 v55, v56, v57
	global_store_dwordx2 v[88:89], v[54:55], off offset:1024
	v_pk_add_f32 v[150:151], v[150:151], 1.0 op_sel_hi:[1,0]
	v_pk_add_f32 v[148:149], v[148:149], 1.0 op_sel_hi:[1,0]
	v_pk_fma_f32 v[52:53], v[52:53], v[150:151], v[134:135]
	v_pk_fma_f32 v[50:51], v[50:51], v[148:149], v[132:133]
	s_nop 0
	v_cvt_pk_bf16_f32 v50, v50, v51
	v_cvt_pk_bf16_f32 v51, v52, v53
	global_store_dwordx2 v[88:89], v[50:51], off offset:1536
	s_andn2_b64 vcc, exec, s[10:11]
	s_cbranch_vccnz .LBB0_162
	s_and_b64 vcc, exec, s[38:39]
	s_cbranch_vccnz .LBB0_172
	v_mov_b32_e32 v50, v47
	v_mov_b32_e32 v51, v48
	v_mov_b32_e32 v52, v46
	v_mov_b32_e32 v53, v49
	v_pk_add_f32 v[50:51], v[50:51], v[52:53]
	v_mov_b32_e32 v52, v43
	v_mov_b32_e32 v53, v44
	v_mov_b32_e32 v54, v42
	v_mov_b32_e32 v55, v45
	v_pk_add_f32 v[52:53], v[52:53], v[54:55]
	v_add_f32_e32 v50, v50, v51
	v_pk_add_f32 v[52:53], v[52:53], v[52:53] op_sel:[0,1] op_sel_hi:[1,0]
	v_add_f32_e32 v50, 0, v50
	v_add_f32_e32 v54, v38, v39
	v_add_f32_e32 v56, v40, v41
	v_mov_b32_e32 v51, v34
	v_mov_b32_e32 v53, v35
	v_mov_b32_e32 v55, v36
	v_mov_b32_e32 v57, v37
	v_pk_add_f32 v[50:51], v[50:51], v[52:53]
	v_pk_add_f32 v[52:53], v[54:55], v[56:57]
	s_nop 0
	v_pk_add_f32 v[50:51], v[50:51], v[52:53]
	v_add_f32_e32 v50, v50, v51
	v_mov_b32_e32 v51, v50
	s_nop 1
	v_add_f32_dpp v51, v51, v51 quad_perm:[1,0,3,2] row_mask:0xf bank_mask:0xf
	s_nop 1
	v_add_f32_dpp v51, v51, v51 quad_perm:[2,3,0,1] row_mask:0xf bank_mask:0xf
	s_nop 1
	v_add_f32_dpp v51, v51, v51 row_half_mirror row_mask:0xf bank_mask:0xf
	s_nop 1
	v_add_f32_dpp v51, v51, v51 row_mirror row_mask:0xf bank_mask:0xf
	s_nop 1
	v_add_f32_dpp v51, v51, v51 row_bcast:15 row_mask:0xa bank_mask:0xf
	s_nop 1
	v_add_f32_dpp v51, v51, v51 row_bcast:31 row_mask:0xc bank_mask:0xf
	s_nop 1
	v_readlane_b32 vcc_lo, v51, 63
	s_nop 1
	v_mov_b32_e32 v51, vcc_lo
	v_fmamk_f32 v49, v51, 0xba800000, v49
	v_fmamk_f32 v47, v51, 0xba800000, v47
	v_fmamk_f32 v48, v51, 0xba800000, v48
	v_fmac_f32_e32 v46, 0xba800000, v51
	v_mul_f32_e32 v50, v47, v47
	v_mul_f32_e32 v58, v49, v49
	v_fmac_f32_e32 v50, v46, v46
	v_fmac_f32_e32 v58, v48, v48
	v_fmamk_f32 v45, v51, 0xba800000, v45
	v_fmamk_f32 v43, v51, 0xba800000, v43
	v_add_f32_e32 v50, v50, v58
	v_fmamk_f32 v44, v51, 0xba800000, v44
	v_fmac_f32_e32 v42, 0xba800000, v51
	v_mul_f32_e32 v58, v43, v43
	v_mul_f32_e32 v59, v45, v45
	v_fmac_f32_e32 v58, v42, v42
	v_fmac_f32_e32 v59, v44, v44
	v_add_f32_e32 v58, v58, v59
	v_fmamk_f32 v41, v51, 0xba800000, v41
	v_fmamk_f32 v39, v51, 0xba800000, v39
	v_add_f32_e32 v50, v50, v58
	v_fmamk_f32 v40, v51, 0xba800000, v40
	v_fmac_f32_e32 v38, 0xba800000, v51
	v_mul_f32_e32 v58, v39, v39
	v_mul_f32_e32 v59, v41, v41
	v_fmac_f32_e32 v58, v38, v38
	v_fmac_f32_e32 v59, v40, v40
	v_add_f32_e32 v58, v58, v59
	v_fmamk_f32 v37, v51, 0xba800000, v37
	v_fmamk_f32 v35, v51, 0xba800000, v35
	v_add_f32_e32 v50, v50, v58
	v_fmamk_f32 v36, v51, 0xba800000, v36
	v_fmac_f32_e32 v34, 0xba800000, v51
	v_mul_f32_e32 v58, v35, v35
	v_mul_f32_e32 v59, v37, v37
	v_fmac_f32_e32 v58, v34, v34
	v_fmac_f32_e32 v59, v36, v36
	v_add_f32_e32 v58, v58, v59
	v_add_f32_e32 v50, v50, v58
	s_nop 1
	v_add_f32_dpp v50, v50, v50 quad_perm:[1,0,3,2] row_mask:0xf bank_mask:0xf
	s_nop 1
	v_add_f32_dpp v50, v50, v50 quad_perm:[2,3,0,1] row_mask:0xf bank_mask:0xf
	s_nop 1
	v_add_f32_dpp v50, v50, v50 row_half_mirror row_mask:0xf bank_mask:0xf
	s_nop 1
	v_add_f32_dpp v50, v50, v50 row_mirror row_mask:0xf bank_mask:0xf
	s_nop 1
	v_add_f32_dpp v50, v50, v50 row_bcast:15 row_mask:0xa bank_mask:0xf
	s_nop 1
	v_add_f32_dpp v50, v50, v50 row_bcast:31 row_mask:0xc bank_mask:0xf
	s_nop 1
	v_readlane_b32 vcc_lo, v50, 63
	s_nop 1
	v_mov_b32_e32 v50, vcc_lo
	v_fmamk_f32 v50, v50, 0x3a800000, v213
	v_mul_f32_e32 v52, 0x4f800000, v50
	v_cmp_gt_f32_e32 vcc, s61, v50
	s_nop 1
	v_cndmask_b32_e32 v50, v50, v52, vcc
	v_sqrt_f32_e32 v52, v50
	s_nop 0
	v_add_u32_e32 v53, -1, v52
	v_fma_f32 v54, -v53, v52, v50
	v_cmp_ge_f32_e64 s[0:1], 0, v54
	v_add_u32_e32 v54, 1, v52
	s_nop 0
	v_cndmask_b32_e64 v53, v52, v53, s[0:1]
	v_fma_f32 v52, -v54, v52, v50
	v_cmp_lt_f32_e64 s[0:1], 0, v52
	s_nop 1
	v_cndmask_b32_e64 v52, v53, v54, s[0:1]
	v_mul_f32_e32 v53, 0x37800000, v52
	v_cndmask_b32_e32 v52, v52, v53, vcc
	v_cmp_class_f32_e32 vcc, v50, v214
	s_nop 1
	v_cndmask_b32_e32 v50, v52, v50, vcc
	v_div_scale_f32 v52, s[0:1], v50, v50, 1.0
	v_rcp_f32_e32 v53, v52
	s_nop 0
	v_fma_f32 v54, -v52, v53, 1.0
	v_fmac_f32_e32 v53, v54, v53
	v_div_scale_f32 v54, vcc, 1.0, v50, 1.0
	v_mul_f32_e32 v55, v54, v53
	v_fma_f32 v56, -v52, v55, v54
	v_fmac_f32_e32 v55, v56, v53
	v_fma_f32 v52, -v52, v55, v54
	v_div_fmas_f32 v52, v52, v53, v55
	v_div_fixup_f32 v50, v52, v50, 1.0
	s_and_saveexec_b64 s[0:1], s[36:37]
	s_cbranch_execz .LBB0_171
	s_add_u32 s10, s90, s34
	v_mul_f32_e32 v52, 0x3a800000, v51
	s_addc_u32 s11, s91, s35
	v_mov_b32_e32 v53, v50
	global_store_dwordx2 v1, v[52:53], s[10:11]

.LBB0_172:
	v_lshl_add_u64 v[60:61], s[90:91], 0, v[76:77]
	v_add_co_u32_e32 v60, vcc, s70, v60
	v_addc_co_u32_e32 v61, vcc, 0, v61, vcc
	s_waitcnt vmcnt(4)
	s_add_i32 s0, s31, s46
	s_min_i32 s0, s0, 0x8000
	s_ashr_i32 s0, s0, 12
	s_mulk_i32 s0, 0xc00
	s_ashr_i32 s1, s0, 31
	s_lshl_b64 s[0:1], s[0:1], 2
	s_add_u32 s0, s19, s0
	s_addc_u32 s1, s28, s1
	s_add_u32 s16, s0, 0x1000
	s_addc_u32 s17, s1, 0
	global_load_dwordx4 v[120:123], v0, s[0:1]
	global_load_dwordx4 v[124:127], v0, s[0:1] offset:1024
	global_load_dwordx4 v[128:131], v0, s[0:1] offset:2048
	global_load_dwordx4 v[132:135], v0, s[0:1] offset:3072
	global_load_dwordx4 v[136:139], v0, s[16:17]
	global_load_dwordx4 v[140:143], v0, s[16:17] offset:1024
	global_load_dwordx4 v[144:147], v0, s[16:17] offset:2048
	global_load_dwordx4 v[148:151], v0, s[16:17] offset:3072
	v_pk_add_f32 v[236:237], v[236:237], 1.0 op_sel_hi:[1,0]
	v_pk_add_f32 v[234:235], v[234:235], 1.0 op_sel_hi:[1,0]
	v_pk_fma_f32 v[48:49], v[48:49], v[236:237], v[220:221]
	v_pk_fma_f32 v[46:47], v[46:47], v[234:235], v[218:219]
	s_nop 0
	v_cvt_pk_bf16_f32 v46, v46, v47
	v_cvt_pk_bf16_f32 v47, v48, v49
	global_store_dwordx2 v[60:61], v[46:47], off
	v_pk_add_f32 v[240:241], v[240:241], 1.0 op_sel_hi:[1,0]
	v_pk_add_f32 v[238:239], v[238:239], 1.0 op_sel_hi:[1,0]
	v_pk_fma_f32 v[44:45], v[44:45], v[240:241], v[224:225]
	v_pk_fma_f32 v[42:43], v[42:43], v[238:239], v[222:223]
	s_nop 0
	v_cvt_pk_bf16_f32 v42, v42, v43
	v_cvt_pk_bf16_f32 v43, v44, v45
	global_store_dwordx2 v[60:61], v[42:43], off offset:512
	v_pk_add_f32 v[244:245], v[244:245], 1.0 op_sel_hi:[1,0]
	v_pk_add_f32 v[242:243], v[242:243], 1.0 op_sel_hi:[1,0]
	v_pk_fma_f32 v[40:41], v[40:41], v[244:245], v[228:229]
	v_pk_fma_f32 v[38:39], v[38:39], v[242:243], v[226:227]
	s_nop 0
	v_cvt_pk_bf16_f32 v38, v38, v39
	v_cvt_pk_bf16_f32 v39, v40, v41
	global_store_dwordx2 v[60:61], v[38:39], off offset:1024
	v_pk_add_f32 v[248:249], v[248:249], 1.0 op_sel_hi:[1,0]
	v_pk_add_f32 v[246:247], v[246:247], 1.0 op_sel_hi:[1,0]
	v_pk_fma_f32 v[36:37], v[36:37], v[248:249], v[232:233]
	v_pk_fma_f32 v[34:35], v[34:35], v[246:247], v[230:231]
	s_nop 0
	v_cvt_pk_bf16_f32 v34, v34, v35
	v_cvt_pk_bf16_f32 v35, v36, v37
	global_store_dwordx2 v[60:61], v[34:35], off offset:1536
	s_andn2_b64 vcc, exec, s[50:51]
	s_cbranch_vccnz .LBB0_162
	s_and_b64 vcc, exec, s[38:39]
	s_add_i32 s10, s31, s46
	s_cbranch_vccnz .LBB0_177
	v_mov_b32_e32 v34, v31
	v_mov_b32_e32 v35, v32
	v_mov_b32_e32 v36, v30
	v_mov_b32_e32 v37, v33
	v_pk_add_f32 v[34:35], v[34:35], v[36:37]
	v_mov_b32_e32 v36, v27
	v_mov_b32_e32 v37, v28
	v_mov_b32_e32 v38, v26
	v_mov_b32_e32 v39, v29
	v_pk_add_f32 v[36:37], v[36:37], v[38:39]
	v_add_f32_e32 v34, v34, v35
	v_pk_add_f32 v[36:37], v[36:37], v[36:37] op_sel:[0,1] op_sel_hi:[1,0]
	v_add_f32_e32 v34, 0, v34
	v_add_f32_e32 v38, v18, v19
	v_add_f32_e32 v40, v20, v21
	v_mov_b32_e32 v35, v22
	v_mov_b32_e32 v37, v23
	v_mov_b32_e32 v39, v24
	v_mov_b32_e32 v41, v25
	v_pk_add_f32 v[34:35], v[34:35], v[36:37]
	v_pk_add_f32 v[36:37], v[38:39], v[40:41]
	s_nop 0
	v_pk_add_f32 v[34:35], v[34:35], v[36:37]
	v_add_f32_e32 v34, v34, v35
	v_mov_b32_e32 v35, v34
	s_nop 1
	v_add_f32_dpp v35, v35, v35 quad_perm:[1,0,3,2] row_mask:0xf bank_mask:0xf
	s_nop 1
	v_add_f32_dpp v35, v35, v35 quad_perm:[2,3,0,1] row_mask:0xf bank_mask:0xf
	s_nop 1
	v_add_f32_dpp v35, v35, v35 row_half_mirror row_mask:0xf bank_mask:0xf
	s_nop 1
	v_add_f32_dpp v35, v35, v35 row_mirror row_mask:0xf bank_mask:0xf
	s_nop 1
	v_add_f32_dpp v35, v35, v35 row_bcast:15 row_mask:0xa bank_mask:0xf
	s_nop 1
	v_add_f32_dpp v35, v35, v35 row_bcast:31 row_mask:0xc bank_mask:0xf
	s_nop 1
	v_readlane_b32 vcc_lo, v35, 63
	s_nop 1
	v_mov_b32_e32 v35, vcc_lo
	v_fmamk_f32 v33, v35, 0xba800000, v33
	v_fmamk_f32 v31, v35, 0xba800000, v31
	v_fmamk_f32 v32, v35, 0xba800000, v32
	v_fmac_f32_e32 v30, 0xba800000, v35
	v_mul_f32_e32 v34, v31, v31
	v_mul_f32_e32 v42, v33, v33
	v_fmac_f32_e32 v34, v30, v30
	v_fmac_f32_e32 v42, v32, v32
	v_fmamk_f32 v29, v35, 0xba800000, v29
	v_fmamk_f32 v27, v35, 0xba800000, v27
	v_add_f32_e32 v34, v34, v42
	v_fmamk_f32 v28, v35, 0xba800000, v28
	v_fmac_f32_e32 v26, 0xba800000, v35
	v_mul_f32_e32 v42, v27, v27
	v_mul_f32_e32 v43, v29, v29
	v_fmac_f32_e32 v42, v26, v26
	v_fmac_f32_e32 v43, v28, v28
	v_add_f32_e32 v42, v42, v43
	v_fmamk_f32 v21, v35, 0xba800000, v21
	v_fmamk_f32 v19, v35, 0xba800000, v19
	v_add_f32_e32 v34, v34, v42
	v_fmamk_f32 v20, v35, 0xba800000, v20
	v_fmac_f32_e32 v18, 0xba800000, v35
	v_mul_f32_e32 v42, v19, v19
	v_mul_f32_e32 v43, v21, v21
	v_fmac_f32_e32 v42, v18, v18
	v_fmac_f32_e32 v43, v20, v20
	v_add_f32_e32 v42, v42, v43
	v_fmamk_f32 v25, v35, 0xba800000, v25
	v_fmamk_f32 v23, v35, 0xba800000, v23
	v_add_f32_e32 v34, v34, v42
	v_fmamk_f32 v24, v35, 0xba800000, v24
	v_fmac_f32_e32 v22, 0xba800000, v35
	v_mul_f32_e32 v42, v23, v23
	v_mul_f32_e32 v43, v25, v25
	v_fmac_f32_e32 v42, v22, v22
	v_fmac_f32_e32 v43, v24, v24
	v_add_f32_e32 v42, v42, v43
	v_add_f32_e32 v34, v34, v42
	s_nop 1
	v_add_f32_dpp v34, v34, v34 quad_perm:[1,0,3,2] row_mask:0xf bank_mask:0xf
	s_nop 1
	v_add_f32_dpp v34, v34, v34 quad_perm:[2,3,0,1] row_mask:0xf bank_mask:0xf
	s_nop 1
	v_add_f32_dpp v34, v34, v34 row_half_mirror row_mask:0xf bank_mask:0xf
	s_nop 1
	v_add_f32_dpp v34, v34, v34 row_mirror row_mask:0xf bank_mask:0xf
	s_nop 1
	v_add_f32_dpp v34, v34, v34 row_bcast:15 row_mask:0xa bank_mask:0xf
	s_nop 1
	v_add_f32_dpp v34, v34, v34 row_bcast:31 row_mask:0xc bank_mask:0xf
	s_nop 1
	v_readlane_b32 vcc_lo, v34, 63
	s_nop 1
	v_mov_b32_e32 v34, vcc_lo
	v_fmamk_f32 v34, v34, 0x3a800000, v213
	v_mul_f32_e32 v36, 0x4f800000, v34
	v_cmp_gt_f32_e32 vcc, s61, v34
	s_nop 1
	v_cndmask_b32_e32 v34, v34, v36, vcc
	v_sqrt_f32_e32 v36, v34
	s_nop 0
	v_add_u32_e32 v37, -1, v36
	v_fma_f32 v38, -v37, v36, v34
	v_cmp_ge_f32_e64 s[0:1], 0, v38
	v_add_u32_e32 v38, 1, v36
	s_nop 0
	v_cndmask_b32_e64 v37, v36, v37, s[0:1]
	v_fma_f32 v36, -v38, v36, v34
	v_cmp_lt_f32_e64 s[0:1], 0, v36
	s_nop 1
	v_cndmask_b32_e64 v36, v37, v38, s[0:1]
	v_mul_f32_e32 v37, 0x37800000, v36
	v_cndmask_b32_e32 v36, v36, v37, vcc
	v_cmp_class_f32_e32 vcc, v34, v214
	s_nop 1
	v_cndmask_b32_e32 v34, v36, v34, vcc
	v_div_scale_f32 v36, s[0:1], v34, v34, 1.0
	v_rcp_f32_e32 v37, v36
	s_nop 0
	v_fma_f32 v38, -v36, v37, 1.0
	v_fmac_f32_e32 v37, v38, v37
	v_div_scale_f32 v38, vcc, 1.0, v34, 1.0
	v_mul_f32_e32 v39, v38, v37
	v_fma_f32 v40, -v36, v39, v38
	v_fmac_f32_e32 v39, v40, v37
	v_fma_f32 v36, -v36, v39, v38
	v_div_fmas_f32 v36, v36, v37, v39
	v_div_fixup_f32 v34, v36, v34, 1.0
	s_and_saveexec_b64 s[0:1], s[36:37]
	s_cbranch_execz .LBB0_176
	s_ashr_i32 s11, s10, 31
	s_lshl_b64 s[50:51], s[10:11], 3
	v_readlane_b32 s11, v252, 20
	s_add_u32 s50, s11, s50
	v_readlane_b32 s11, v252, 21
	v_mul_f32_e32 v36, 0x3a800000, v35
	s_addc_u32 s51, s11, s51
	v_mov_b32_e32 v37, v34
	global_store_dwordx2 v1, v[36:37], s[50:51]

.LBB0_177:
	s_ashr_i32 s11, s10, 31
	s_lshl_b64 s[10:11], s[10:11], 11
	v_lshl_add_u64 v[42:43], v[72:73], 0, s[10:11]
	s_waitcnt vmcnt(4)
	s_mul_i32 s0, s12, 3
	s_add_i32 s0, s0, s46
	s_min_i32 s0, s0, 0x8000
	s_ashr_i32 s0, s0, 12
	s_mulk_i32 s0, 0xc00
	s_ashr_i32 s1, s0, 31
	s_lshl_b64 s[0:1], s[0:1], 2
	s_add_u32 s0, s19, s0
	s_addc_u32 s1, s28, s1
	s_add_u32 s16, s0, 0x1000
	s_addc_u32 s17, s1, 0
	global_load_dwordx4 v[218:221], v0, s[0:1]
	global_load_dwordx4 v[222:225], v0, s[0:1] offset:1024
	global_load_dwordx4 v[226:229], v0, s[0:1] offset:2048
	global_load_dwordx4 v[230:233], v0, s[0:1] offset:3072
	global_load_dwordx4 v[234:237], v0, s[16:17]
	global_load_dwordx4 v[238:241], v0, s[16:17] offset:1024
	global_load_dwordx4 v[242:245], v0, s[16:17] offset:2048
	global_load_dwordx4 v[246:249], v0, s[16:17] offset:3072
	v_pk_add_f32 v[138:139], v[138:139], 1.0 op_sel_hi:[1,0]
	v_pk_add_f32 v[136:137], v[136:137], 1.0 op_sel_hi:[1,0]
	v_pk_fma_f32 v[32:33], v[32:33], v[138:139], v[122:123]
	v_pk_fma_f32 v[30:31], v[30:31], v[136:137], v[120:121]
	s_nop 0
	v_cvt_pk_bf16_f32 v30, v30, v31
	v_cvt_pk_bf16_f32 v31, v32, v33
	global_store_dwordx2 v[42:43], v[30:31], off
	v_pk_add_f32 v[142:143], v[142:143], 1.0 op_sel_hi:[1,0]
	v_pk_add_f32 v[140:141], v[140:141], 1.0 op_sel_hi:[1,0]
	v_pk_fma_f32 v[28:29], v[28:29], v[142:143], v[126:127]
	v_pk_fma_f32 v[26:27], v[26:27], v[140:141], v[124:125]
	s_nop 0
	v_cvt_pk_bf16_f32 v26, v26, v27
	v_cvt_pk_bf16_f32 v27, v28, v29
	global_store_dwordx2 v[42:43], v[26:27], off offset:512
	v_pk_add_f32 v[146:147], v[146:147], 1.0 op_sel_hi:[1,0]
	v_pk_add_f32 v[144:145], v[144:145], 1.0 op_sel_hi:[1,0]
	v_pk_fma_f32 v[20:21], v[20:21], v[146:147], v[130:131]
	v_pk_fma_f32 v[18:19], v[18:19], v[144:145], v[128:129]
	s_nop 0
	v_cvt_pk_bf16_f32 v18, v18, v19
	v_cvt_pk_bf16_f32 v19, v20, v21
	global_store_dwordx2 v[42:43], v[18:19], off offset:1024
	v_pk_add_f32 v[150:151], v[150:151], 1.0 op_sel_hi:[1,0]
	v_pk_add_f32 v[148:149], v[148:149], 1.0 op_sel_hi:[1,0]
	v_pk_fma_f32 v[24:25], v[24:25], v[150:151], v[134:135]
	v_pk_fma_f32 v[22:23], v[22:23], v[148:149], v[132:133]
	s_nop 0
	v_cvt_pk_bf16_f32 v22, v22, v23
	v_cvt_pk_bf16_f32 v23, v24, v25
	global_store_dwordx2 v[42:43], v[22:23], off offset:1536
	s_andn2_b64 vcc, exec, s[8:9]
	s_cbranch_vccnz .LBB0_162
	s_mul_i32 s0, s12, 3
	s_and_b64 vcc, exec, s[38:39]
	s_add_i32 s8, s0, s46
	s_cbranch_vccnz .LBB0_161
	v_mov_b32_e32 v18, v15
	v_mov_b32_e32 v19, v16
	v_mov_b32_e32 v20, v14
	v_mov_b32_e32 v21, v17
	v_pk_add_f32 v[18:19], v[18:19], v[20:21]
	v_mov_b32_e32 v20, v11
	v_mov_b32_e32 v21, v12
	v_mov_b32_e32 v22, v10
	v_mov_b32_e32 v23, v13
	v_pk_add_f32 v[20:21], v[20:21], v[22:23]
	v_add_f32_e32 v18, v18, v19
	v_pk_add_f32 v[20:21], v[20:21], v[20:21] op_sel:[0,1] op_sel_hi:[1,0]
	v_add_f32_e32 v18, 0, v18
	v_add_f32_e32 v22, v2, v3
	v_add_f32_e32 v24, v4, v5
	v_mov_b32_e32 v19, v6
	v_mov_b32_e32 v21, v7
	v_mov_b32_e32 v23, v8
	v_mov_b32_e32 v25, v9
	v_pk_add_f32 v[18:19], v[18:19], v[20:21]
	v_pk_add_f32 v[20:21], v[22:23], v[24:25]
	s_nop 0
	v_pk_add_f32 v[18:19], v[18:19], v[20:21]
	v_add_f32_e32 v18, v18, v19
	v_mov_b32_e32 v19, v18
	s_nop 1
	v_add_f32_dpp v19, v19, v19 quad_perm:[1,0,3,2] row_mask:0xf bank_mask:0xf
	s_nop 1
	v_add_f32_dpp v19, v19, v19 quad_perm:[2,3,0,1] row_mask:0xf bank_mask:0xf
	s_nop 1
	v_add_f32_dpp v19, v19, v19 row_half_mirror row_mask:0xf bank_mask:0xf
	s_nop 1
	v_add_f32_dpp v19, v19, v19 row_mirror row_mask:0xf bank_mask:0xf
	s_nop 1
	v_add_f32_dpp v19, v19, v19 row_bcast:15 row_mask:0xa bank_mask:0xf
	s_nop 1
	v_add_f32_dpp v19, v19, v19 row_bcast:31 row_mask:0xc bank_mask:0xf
	s_nop 1
	v_readlane_b32 vcc_lo, v19, 63
	s_nop 1
	v_mov_b32_e32 v19, vcc_lo
	v_fmamk_f32 v17, v19, 0xba800000, v17
	v_fmamk_f32 v15, v19, 0xba800000, v15
	v_fmamk_f32 v16, v19, 0xba800000, v16
	v_fmac_f32_e32 v14, 0xba800000, v19
	v_mul_f32_e32 v18, v15, v15
	v_mul_f32_e32 v26, v17, v17
	v_fmac_f32_e32 v18, v14, v14
	v_fmac_f32_e32 v26, v16, v16
	v_fmamk_f32 v13, v19, 0xba800000, v13
	v_fmamk_f32 v11, v19, 0xba800000, v11
	v_add_f32_e32 v18, v18, v26
	v_fmamk_f32 v12, v19, 0xba800000, v12
	v_fmac_f32_e32 v10, 0xba800000, v19
	v_mul_f32_e32 v26, v11, v11
	v_mul_f32_e32 v27, v13, v13
	v_fmac_f32_e32 v26, v10, v10
	v_fmac_f32_e32 v27, v12, v12
	v_add_f32_e32 v26, v26, v27
	v_fmamk_f32 v5, v19, 0xba800000, v5
	v_fmamk_f32 v3, v19, 0xba800000, v3
	v_add_f32_e32 v18, v18, v26
	v_fmamk_f32 v4, v19, 0xba800000, v4
	v_fmac_f32_e32 v2, 0xba800000, v19
	v_mul_f32_e32 v26, v3, v3
	v_mul_f32_e32 v27, v5, v5
	v_fmac_f32_e32 v26, v2, v2
	v_fmac_f32_e32 v27, v4, v4
	v_add_f32_e32 v26, v26, v27
	v_fmamk_f32 v9, v19, 0xba800000, v9
	v_fmamk_f32 v7, v19, 0xba800000, v7
	v_add_f32_e32 v18, v18, v26
	v_fmamk_f32 v8, v19, 0xba800000, v8
	v_fmac_f32_e32 v6, 0xba800000, v19
	v_mul_f32_e32 v26, v7, v7
	v_mul_f32_e32 v27, v9, v9
	v_fmac_f32_e32 v26, v6, v6
	v_fmac_f32_e32 v27, v8, v8
	v_add_f32_e32 v26, v26, v27
	v_add_f32_e32 v18, v18, v26
	s_nop 1
	v_add_f32_dpp v18, v18, v18 quad_perm:[1,0,3,2] row_mask:0xf bank_mask:0xf
	s_nop 1
	v_add_f32_dpp v18, v18, v18 quad_perm:[2,3,0,1] row_mask:0xf bank_mask:0xf
	s_nop 1
	v_add_f32_dpp v18, v18, v18 row_half_mirror row_mask:0xf bank_mask:0xf
	s_nop 1
	v_add_f32_dpp v18, v18, v18 row_mirror row_mask:0xf bank_mask:0xf
	s_nop 1
	v_add_f32_dpp v18, v18, v18 row_bcast:15 row_mask:0xa bank_mask:0xf
	s_nop 1
	v_add_f32_dpp v18, v18, v18 row_bcast:31 row_mask:0xc bank_mask:0xf
	s_nop 1
	v_readlane_b32 vcc_lo, v18, 63
	s_nop 1
	v_mov_b32_e32 v18, vcc_lo
	v_fmamk_f32 v18, v18, 0x3a800000, v213
	v_mul_f32_e32 v20, 0x4f800000, v18
	v_cmp_gt_f32_e32 vcc, s61, v18
	s_nop 1
	v_cndmask_b32_e32 v18, v18, v20, vcc
	v_sqrt_f32_e32 v20, v18
	s_nop 0
	v_add_u32_e32 v21, -1, v20
	v_fma_f32 v22, -v21, v20, v18
	v_cmp_ge_f32_e64 s[0:1], 0, v22
	v_add_u32_e32 v22, 1, v20
	s_nop 0
	v_cndmask_b32_e64 v21, v20, v21, s[0:1]
	v_fma_f32 v20, -v22, v20, v18
	v_cmp_lt_f32_e64 s[0:1], 0, v20
	s_nop 1
	v_cndmask_b32_e64 v20, v21, v22, s[0:1]
	v_mul_f32_e32 v21, 0x37800000, v20
	v_cndmask_b32_e32 v20, v20, v21, vcc
	v_cmp_class_f32_e32 vcc, v18, v214
	s_nop 1
	v_cndmask_b32_e32 v18, v20, v18, vcc
	v_div_scale_f32 v20, s[0:1], v18, v18, 1.0
	v_rcp_f32_e32 v21, v20
	s_nop 0
	v_fma_f32 v22, -v20, v21, 1.0
	v_fmac_f32_e32 v21, v22, v21
	v_div_scale_f32 v22, vcc, 1.0, v18, 1.0
	v_mul_f32_e32 v23, v22, v21
	v_fma_f32 v24, -v20, v23, v22
	v_fmac_f32_e32 v23, v24, v21
	v_fma_f32 v20, -v20, v23, v22
	v_div_fmas_f32 v20, v20, v21, v23
	v_div_fixup_f32 v18, v20, v18, 1.0
	s_and_saveexec_b64 s[0:1], s[36:37]
	s_cbranch_execz .LBB0_160
	s_ashr_i32 s9, s8, 31
	s_lshl_b64 s[10:11], s[8:9], 3
	v_readlane_b32 s9, v252, 20
	s_add_u32 s10, s9, s10
	v_readlane_b32 s9, v252, 21
	v_mul_f32_e32 v20, 0x3a800000, v19
	s_addc_u32 s11, s9, s11
	v_mov_b32_e32 v21, v18
	global_store_dwordx2 v1, v[20:21], s[10:11]
	s_branch .LBB0_160
	s_nop 0
